# S5 output GEMM epilogue (GELU) rewritten by hand: argument as a*(c1+c2*a^2) with folded constants, packed f32 ops, running store pointers
# speedup vs baseline: 1.0059x; 1.0012x over previous
.LBB0_916:
	s_andn2_b64 vcc, exec, s[0:1]
	s_cbranch_vccnz .LBB0_929
	s_cmp_gt_i32 s66, 5
	s_mov_b64 s[0:1], -1
	s_cbranch_scc0 .LBB0_919
	s_waitcnt lgkmcnt(0)
	v_ashrrev_i32_e32 v83, 2, v192
	v_and_b32_e32 v82, 15, v192
	v_and_b32_e32 v83, 0xffffffc0, v83
	v_add3_u32 v132, v82, s30, v83
	v_ashrrev_i32_e32 v133, 31, v132
	v_lshrrev_b32_e32 v80, 1, v192
	v_and_b32_e32 v82, 0x60, v80
	v_and_b32_e32 v80, 24, v80
	v_add3_u32 v80, v82, s6, v80
	v_lshlrev_b64 v[82:83], 15, v[132:133]
	s_lshl_b32 s0, s78, 4
	s_ashr_i32 s1, s0, 31
	v_lshl_add_u64 v[82:83], s[94:95], 0, v[82:83]
	s_lshl_b64 s[0:1], s[0:1], 1
	s_nop 0
	v_lshl_add_u64 v[144:145], v[82:83], 0, s[0:1]
	v_ashrrev_i32_e32 v82, 4, v80
	v_ashrrev_i32_e32 v83, 31, v82
	v_and_b32_e32 v146, 15, v80
	v_lshlrev_b64 v[82:83], 10, v[82:83]
	v_lshl_add_u64 v[144:145], v[144:145], 0, v[82:83]
	v_lshlrev_b32_e32 v146, 1, v146
	v_mov_b32_e32 v147, v81
	v_lshl_add_u64 v[144:145], v[144:145], 0, v[146:147]
	s_mov_b64 vcc, 0x2000
	s_nop 0
	v_lshl_add_u64 v[148:149], v[144:145], 0, vcc
	v_mov_b32_e32 v244, 0xbdd2d3e7
	v_mov_b32_e32 v246, 0xc0135761
	v_pk_mul_f32 v[136:137], v[128:129], v[128:129]
	v_pk_mul_f32 v[138:139], v[130:131], v[130:131]
	v_pk_mul_f32 v[140:141], v[124:125], v[124:125]
	v_pk_mul_f32 v[142:143], v[126:127], v[126:127]
	v_pk_fma_f32 v[136:137], v[136:137], v[244:245], v[246:247] op_sel_hi:[1,0,0]
	v_pk_fma_f32 v[138:139], v[138:139], v[244:245], v[246:247] op_sel_hi:[1,0,0]
	v_pk_fma_f32 v[140:141], v[140:141], v[244:245], v[246:247] op_sel_hi:[1,0,0]
	v_pk_fma_f32 v[142:143], v[142:143], v[244:245], v[246:247] op_sel_hi:[1,0,0]
	v_pk_mul_f32 v[136:137], v[136:137], v[128:129]
	v_pk_mul_f32 v[138:139], v[138:139], v[130:131]
	v_pk_mul_f32 v[140:141], v[140:141], v[124:125]
	v_pk_mul_f32 v[142:143], v[142:143], v[126:127]
	v_exp_f32_e32 v136, v136
	v_exp_f32_e32 v137, v137
	v_exp_f32_e32 v138, v138
	v_exp_f32_e32 v139, v139
	v_exp_f32_e32 v140, v140
	v_exp_f32_e32 v141, v141
	v_exp_f32_e32 v142, v142
	v_exp_f32_e32 v143, v143
	s_nop 0
	v_pk_add_f32 v[136:137], v[136:137], 1.0 op_sel_hi:[1,0]
	v_pk_add_f32 v[138:139], v[138:139], 1.0 op_sel_hi:[1,0]
	v_pk_add_f32 v[140:141], v[140:141], 1.0 op_sel_hi:[1,0]
	v_pk_add_f32 v[142:143], v[142:143], 1.0 op_sel_hi:[1,0]
	v_rcp_f32_e32 v136, v136
	v_rcp_f32_e32 v137, v137
	v_rcp_f32_e32 v138, v138
	v_rcp_f32_e32 v139, v139
	v_rcp_f32_e32 v140, v140
	v_rcp_f32_e32 v141, v141
	v_rcp_f32_e32 v142, v142
	v_rcp_f32_e32 v143, v143
	s_nop 0
	v_pk_mul_f32 v[128:129], v[128:129], v[136:137]
	v_pk_mul_f32 v[130:131], v[130:131], v[138:139]
	v_pk_mul_f32 v[124:125], v[124:125], v[140:141]
	v_pk_mul_f32 v[126:127], v[126:127], v[142:143]
	v_cvt_pk_bf16_f32 v128, v128, v129
	v_cvt_pk_bf16_f32 v129, v130, v131
	v_cvt_pk_bf16_f32 v130, v124, v125
	v_cvt_pk_bf16_f32 v131, v126, v127
	global_store_dwordx4 v[144:145], v[128:131], off
	v_pk_mul_f32 v[136:137], v[120:121], v[120:121]
	v_pk_mul_f32 v[138:139], v[122:123], v[122:123]
	v_pk_mul_f32 v[140:141], v[116:117], v[116:117]
	v_pk_mul_f32 v[142:143], v[118:119], v[118:119]
	v_pk_fma_f32 v[136:137], v[136:137], v[244:245], v[246:247] op_sel_hi:[1,0,0]
	v_pk_fma_f32 v[138:139], v[138:139], v[244:245], v[246:247] op_sel_hi:[1,0,0]
	v_pk_fma_f32 v[140:141], v[140:141], v[244:245], v[246:247] op_sel_hi:[1,0,0]
	v_pk_fma_f32 v[142:143], v[142:143], v[244:245], v[246:247] op_sel_hi:[1,0,0]
	v_pk_mul_f32 v[136:137], v[136:137], v[120:121]
	v_pk_mul_f32 v[138:139], v[138:139], v[122:123]
	v_pk_mul_f32 v[140:141], v[140:141], v[116:117]
	v_pk_mul_f32 v[142:143], v[142:143], v[118:119]
	v_exp_f32_e32 v136, v136
	v_exp_f32_e32 v137, v137
	v_exp_f32_e32 v138, v138
	v_exp_f32_e32 v139, v139
	v_exp_f32_e32 v140, v140
	v_exp_f32_e32 v141, v141
	v_exp_f32_e32 v142, v142
	v_exp_f32_e32 v143, v143
	s_nop 0
	v_pk_add_f32 v[136:137], v[136:137], 1.0 op_sel_hi:[1,0]
	v_pk_add_f32 v[138:139], v[138:139], 1.0 op_sel_hi:[1,0]
	v_pk_add_f32 v[140:141], v[140:141], 1.0 op_sel_hi:[1,0]
	v_pk_add_f32 v[142:143], v[142:143], 1.0 op_sel_hi:[1,0]
	v_rcp_f32_e32 v136, v136
	v_rcp_f32_e32 v137, v137
	v_rcp_f32_e32 v138, v138
	v_rcp_f32_e32 v139, v139
	v_rcp_f32_e32 v140, v140
	v_rcp_f32_e32 v141, v141
	v_rcp_f32_e32 v142, v142
	v_rcp_f32_e32 v143, v143
	s_nop 0
	v_pk_mul_f32 v[120:121], v[120:121], v[136:137]
	v_pk_mul_f32 v[122:123], v[122:123], v[138:139]
	v_pk_mul_f32 v[116:117], v[116:117], v[140:141]
	v_pk_mul_f32 v[118:119], v[118:119], v[142:143]
	v_cvt_pk_bf16_f32 v120, v120, v121
	v_cvt_pk_bf16_f32 v121, v122, v123
	v_cvt_pk_bf16_f32 v122, v116, v117
	v_cvt_pk_bf16_f32 v123, v118, v119
	global_store_dwordx4 v[148:149], v[120:123], off
	s_mov_b64 vcc, 0x80000
	s_nop 0
	v_lshl_add_u64 v[144:145], v[144:145], 0, vcc
	v_lshl_add_u64 v[148:149], v[148:149], 0, vcc
	v_pk_mul_f32 v[136:137], v[112:113], v[112:113]
	v_pk_mul_f32 v[138:139], v[114:115], v[114:115]
	v_pk_mul_f32 v[140:141], v[108:109], v[108:109]
	v_pk_mul_f32 v[142:143], v[110:111], v[110:111]
	v_pk_fma_f32 v[136:137], v[136:137], v[244:245], v[246:247] op_sel_hi:[1,0,0]
	v_pk_fma_f32 v[138:139], v[138:139], v[244:245], v[246:247] op_sel_hi:[1,0,0]
	v_pk_fma_f32 v[140:141], v[140:141], v[244:245], v[246:247] op_sel_hi:[1,0,0]
	v_pk_fma_f32 v[142:143], v[142:143], v[244:245], v[246:247] op_sel_hi:[1,0,0]
	v_pk_mul_f32 v[136:137], v[136:137], v[112:113]
	v_pk_mul_f32 v[138:139], v[138:139], v[114:115]
	v_pk_mul_f32 v[140:141], v[140:141], v[108:109]
	v_pk_mul_f32 v[142:143], v[142:143], v[110:111]
	v_exp_f32_e32 v136, v136
	v_exp_f32_e32 v137, v137
	v_exp_f32_e32 v138, v138
	v_exp_f32_e32 v139, v139
	v_exp_f32_e32 v140, v140
	v_exp_f32_e32 v141, v141
	v_exp_f32_e32 v142, v142
	v_exp_f32_e32 v143, v143
	s_nop 0
	v_pk_add_f32 v[136:137], v[136:137], 1.0 op_sel_hi:[1,0]
	v_pk_add_f32 v[138:139], v[138:139], 1.0 op_sel_hi:[1,0]
	v_pk_add_f32 v[140:141], v[140:141], 1.0 op_sel_hi:[1,0]
	v_pk_add_f32 v[142:143], v[142:143], 1.0 op_sel_hi:[1,0]
	v_rcp_f32_e32 v136, v136
	v_rcp_f32_e32 v137, v137
	v_rcp_f32_e32 v138, v138
	v_rcp_f32_e32 v139, v139
	v_rcp_f32_e32 v140, v140
	v_rcp_f32_e32 v141, v141
	v_rcp_f32_e32 v142, v142
	v_rcp_f32_e32 v143, v143
	s_nop 0
	v_pk_mul_f32 v[112:113], v[112:113], v[136:137]
	v_pk_mul_f32 v[114:115], v[114:115], v[138:139]
	v_pk_mul_f32 v[108:109], v[108:109], v[140:141]
	v_pk_mul_f32 v[110:111], v[110:111], v[142:143]
	v_cvt_pk_bf16_f32 v112, v112, v113
	v_cvt_pk_bf16_f32 v113, v114, v115
	v_cvt_pk_bf16_f32 v114, v108, v109
	v_cvt_pk_bf16_f32 v115, v110, v111
	global_store_dwordx4 v[144:145], v[112:115], off
	v_pk_mul_f32 v[136:137], v[104:105], v[104:105]
	v_pk_mul_f32 v[138:139], v[106:107], v[106:107]
	v_pk_mul_f32 v[140:141], v[100:101], v[100:101]
	v_pk_mul_f32 v[142:143], v[102:103], v[102:103]
	v_pk_fma_f32 v[136:137], v[136:137], v[244:245], v[246:247] op_sel_hi:[1,0,0]
	v_pk_fma_f32 v[138:139], v[138:139], v[244:245], v[246:247] op_sel_hi:[1,0,0]
	v_pk_fma_f32 v[140:141], v[140:141], v[244:245], v[246:247] op_sel_hi:[1,0,0]
	v_pk_fma_f32 v[142:143], v[142:143], v[244:245], v[246:247] op_sel_hi:[1,0,0]
	v_pk_mul_f32 v[136:137], v[136:137], v[104:105]
	v_pk_mul_f32 v[138:139], v[138:139], v[106:107]
	v_pk_mul_f32 v[140:141], v[140:141], v[100:101]
	v_pk_mul_f32 v[142:143], v[142:143], v[102:103]
	v_exp_f32_e32 v136, v136
	v_exp_f32_e32 v137, v137
	v_exp_f32_e32 v138, v138
	v_exp_f32_e32 v139, v139
	v_exp_f32_e32 v140, v140
	v_exp_f32_e32 v141, v141
	v_exp_f32_e32 v142, v142
	v_exp_f32_e32 v143, v143
	s_nop 0
	v_pk_add_f32 v[136:137], v[136:137], 1.0 op_sel_hi:[1,0]
	v_pk_add_f32 v[138:139], v[138:139], 1.0 op_sel_hi:[1,0]
	v_pk_add_f32 v[140:141], v[140:141], 1.0 op_sel_hi:[1,0]
	v_pk_add_f32 v[142:143], v[142:143], 1.0 op_sel_hi:[1,0]
	v_rcp_f32_e32 v136, v136
	v_rcp_f32_e32 v137, v137
	v_rcp_f32_e32 v138, v138
	v_rcp_f32_e32 v139, v139
	v_rcp_f32_e32 v140, v140
	v_rcp_f32_e32 v141, v141
	v_rcp_f32_e32 v142, v142
	v_rcp_f32_e32 v143, v143
	s_nop 0
	v_pk_mul_f32 v[104:105], v[104:105], v[136:137]
	v_pk_mul_f32 v[106:107], v[106:107], v[138:139]
	v_pk_mul_f32 v[100:101], v[100:101], v[140:141]
	v_pk_mul_f32 v[102:103], v[102:103], v[142:143]
	v_cvt_pk_bf16_f32 v104, v104, v105
	v_cvt_pk_bf16_f32 v105, v106, v107
	v_cvt_pk_bf16_f32 v106, v100, v101
	v_cvt_pk_bf16_f32 v107, v102, v103
	global_store_dwordx4 v[148:149], v[104:107], off
	s_mov_b64 vcc, 0x80000
	s_nop 0
	v_lshl_add_u64 v[144:145], v[144:145], 0, vcc
	v_lshl_add_u64 v[148:149], v[148:149], 0, vcc
	v_pk_mul_f32 v[136:137], v[96:97], v[96:97]
	v_pk_mul_f32 v[138:139], v[98:99], v[98:99]
	v_pk_mul_f32 v[140:141], v[92:93], v[92:93]
	v_pk_mul_f32 v[142:143], v[94:95], v[94:95]
	v_pk_fma_f32 v[136:137], v[136:137], v[244:245], v[246:247] op_sel_hi:[1,0,0]
	v_pk_fma_f32 v[138:139], v[138:139], v[244:245], v[246:247] op_sel_hi:[1,0,0]
	v_pk_fma_f32 v[140:141], v[140:141], v[244:245], v[246:247] op_sel_hi:[1,0,0]
	v_pk_fma_f32 v[142:143], v[142:143], v[244:245], v[246:247] op_sel_hi:[1,0,0]
	v_pk_mul_f32 v[136:137], v[136:137], v[96:97]
	v_pk_mul_f32 v[138:139], v[138:139], v[98:99]
	v_pk_mul_f32 v[140:141], v[140:141], v[92:93]
	v_pk_mul_f32 v[142:143], v[142:143], v[94:95]
	v_exp_f32_e32 v136, v136
	v_exp_f32_e32 v137, v137
	v_exp_f32_e32 v138, v138
	v_exp_f32_e32 v139, v139
	v_exp_f32_e32 v140, v140
	v_exp_f32_e32 v141, v141
	v_exp_f32_e32 v142, v142
	v_exp_f32_e32 v143, v143
	s_nop 0
	v_pk_add_f32 v[136:137], v[136:137], 1.0 op_sel_hi:[1,0]
	v_pk_add_f32 v[138:139], v[138:139], 1.0 op_sel_hi:[1,0]
	v_pk_add_f32 v[140:141], v[140:141], 1.0 op_sel_hi:[1,0]
	v_pk_add_f32 v[142:143], v[142:143], 1.0 op_sel_hi:[1,0]
	v_rcp_f32_e32 v136, v136
	v_rcp_f32_e32 v137, v137
	v_rcp_f32_e32 v138, v138
	v_rcp_f32_e32 v139, v139
	v_rcp_f32_e32 v140, v140
	v_rcp_f32_e32 v141, v141
	v_rcp_f32_e32 v142, v142
	v_rcp_f32_e32 v143, v143
	s_nop 0
	v_pk_mul_f32 v[96:97], v[96:97], v[136:137]
	v_pk_mul_f32 v[98:99], v[98:99], v[138:139]
	v_pk_mul_f32 v[92:93], v[92:93], v[140:141]
	v_pk_mul_f32 v[94:95], v[94:95], v[142:143]
	v_cvt_pk_bf16_f32 v96, v96, v97
	v_cvt_pk_bf16_f32 v97, v98, v99
	v_cvt_pk_bf16_f32 v98, v92, v93
	v_cvt_pk_bf16_f32 v99, v94, v95
	global_store_dwordx4 v[144:145], v[96:99], off
	v_pk_mul_f32 v[136:137], v[88:89], v[88:89]
	v_pk_mul_f32 v[138:139], v[90:91], v[90:91]
	v_pk_mul_f32 v[140:141], v[84:85], v[84:85]
	v_pk_mul_f32 v[142:143], v[86:87], v[86:87]
	v_pk_fma_f32 v[136:137], v[136:137], v[244:245], v[246:247] op_sel_hi:[1,0,0]
	v_pk_fma_f32 v[138:139], v[138:139], v[244:245], v[246:247] op_sel_hi:[1,0,0]
	v_pk_fma_f32 v[140:141], v[140:141], v[244:245], v[246:247] op_sel_hi:[1,0,0]
	v_pk_fma_f32 v[142:143], v[142:143], v[244:245], v[246:247] op_sel_hi:[1,0,0]
	v_pk_mul_f32 v[136:137], v[136:137], v[88:89]
	v_pk_mul_f32 v[138:139], v[138:139], v[90:91]
	v_pk_mul_f32 v[140:141], v[140:141], v[84:85]
	v_pk_mul_f32 v[142:143], v[142:143], v[86:87]
	v_exp_f32_e32 v136, v136
	v_exp_f32_e32 v137, v137
	v_exp_f32_e32 v138, v138
	v_exp_f32_e32 v139, v139
	v_exp_f32_e32 v140, v140
	v_exp_f32_e32 v141, v141
	v_exp_f32_e32 v142, v142
	v_exp_f32_e32 v143, v143
	s_nop 0
	v_pk_add_f32 v[136:137], v[136:137], 1.0 op_sel_hi:[1,0]
	v_pk_add_f32 v[138:139], v[138:139], 1.0 op_sel_hi:[1,0]
	v_pk_add_f32 v[140:141], v[140:141], 1.0 op_sel_hi:[1,0]
	v_pk_add_f32 v[142:143], v[142:143], 1.0 op_sel_hi:[1,0]
	v_rcp_f32_e32 v136, v136
	v_rcp_f32_e32 v137, v137
	v_rcp_f32_e32 v138, v138
	v_rcp_f32_e32 v139, v139
	v_rcp_f32_e32 v140, v140
	v_rcp_f32_e32 v141, v141
	v_rcp_f32_e32 v142, v142
	v_rcp_f32_e32 v143, v143
	s_nop 0
	v_pk_mul_f32 v[88:89], v[88:89], v[136:137]
	v_pk_mul_f32 v[90:91], v[90:91], v[138:139]
	v_pk_mul_f32 v[84:85], v[84:85], v[140:141]
	v_pk_mul_f32 v[86:87], v[86:87], v[142:143]
	v_cvt_pk_bf16_f32 v88, v88, v89
	v_cvt_pk_bf16_f32 v89, v90, v91
	v_cvt_pk_bf16_f32 v90, v84, v85
	v_cvt_pk_bf16_f32 v91, v86, v87
	global_store_dwordx4 v[148:149], v[88:91], off
	s_mov_b64 vcc, 0x80000
	s_nop 0
	v_lshl_add_u64 v[144:145], v[144:145], 0, vcc
	v_lshl_add_u64 v[148:149], v[148:149], 0, vcc
	v_pk_mul_f32 v[136:137], v[76:77], v[76:77]
	v_pk_mul_f32 v[138:139], v[78:79], v[78:79]
	v_pk_mul_f32 v[140:141], v[72:73], v[72:73]
	v_pk_mul_f32 v[142:143], v[74:75], v[74:75]
	v_pk_fma_f32 v[136:137], v[136:137], v[244:245], v[246:247] op_sel_hi:[1,0,0]
	v_pk_fma_f32 v[138:139], v[138:139], v[244:245], v[246:247] op_sel_hi:[1,0,0]
	v_pk_fma_f32 v[140:141], v[140:141], v[244:245], v[246:247] op_sel_hi:[1,0,0]
	v_pk_fma_f32 v[142:143], v[142:143], v[244:245], v[246:247] op_sel_hi:[1,0,0]
	v_pk_mul_f32 v[136:137], v[136:137], v[76:77]
	v_pk_mul_f32 v[138:139], v[138:139], v[78:79]
	v_pk_mul_f32 v[140:141], v[140:141], v[72:73]
	v_pk_mul_f32 v[142:143], v[142:143], v[74:75]
	v_exp_f32_e32 v136, v136
	v_exp_f32_e32 v137, v137
	v_exp_f32_e32 v138, v138
	v_exp_f32_e32 v139, v139
	v_exp_f32_e32 v140, v140
	v_exp_f32_e32 v141, v141
	v_exp_f32_e32 v142, v142
	v_exp_f32_e32 v143, v143
	s_nop 0
	v_pk_add_f32 v[136:137], v[136:137], 1.0 op_sel_hi:[1,0]
	v_pk_add_f32 v[138:139], v[138:139], 1.0 op_sel_hi:[1,0]
	v_pk_add_f32 v[140:141], v[140:141], 1.0 op_sel_hi:[1,0]
	v_pk_add_f32 v[142:143], v[142:143], 1.0 op_sel_hi:[1,0]
	v_rcp_f32_e32 v136, v136
	v_rcp_f32_e32 v137, v137
	v_rcp_f32_e32 v138, v138
	v_rcp_f32_e32 v139, v139
	v_rcp_f32_e32 v140, v140
	v_rcp_f32_e32 v141, v141
	v_rcp_f32_e32 v142, v142
	v_rcp_f32_e32 v143, v143
	s_nop 0
	v_pk_mul_f32 v[76:77], v[76:77], v[136:137]
	v_pk_mul_f32 v[78:79], v[78:79], v[138:139]
	v_pk_mul_f32 v[72:73], v[72:73], v[140:141]
	v_pk_mul_f32 v[74:75], v[74:75], v[142:143]
	v_cvt_pk_bf16_f32 v76, v76, v77
	v_cvt_pk_bf16_f32 v77, v78, v79
	v_cvt_pk_bf16_f32 v78, v72, v73
	v_cvt_pk_bf16_f32 v79, v74, v75
	global_store_dwordx4 v[144:145], v[76:79], off
	v_pk_mul_f32 v[136:137], v[68:69], v[68:69]
	v_pk_mul_f32 v[138:139], v[70:71], v[70:71]
	v_pk_mul_f32 v[140:141], v[64:65], v[64:65]
	v_pk_mul_f32 v[142:143], v[66:67], v[66:67]
	v_pk_fma_f32 v[136:137], v[136:137], v[244:245], v[246:247] op_sel_hi:[1,0,0]
	v_pk_fma_f32 v[138:139], v[138:139], v[244:245], v[246:247] op_sel_hi:[1,0,0]
	v_pk_fma_f32 v[140:141], v[140:141], v[244:245], v[246:247] op_sel_hi:[1,0,0]
	v_pk_fma_f32 v[142:143], v[142:143], v[244:245], v[246:247] op_sel_hi:[1,0,0]
	v_pk_mul_f32 v[136:137], v[136:137], v[68:69]
	v_pk_mul_f32 v[138:139], v[138:139], v[70:71]
	v_pk_mul_f32 v[140:141], v[140:141], v[64:65]
	v_pk_mul_f32 v[142:143], v[142:143], v[66:67]
	v_exp_f32_e32 v136, v136
	v_exp_f32_e32 v137, v137
	v_exp_f32_e32 v138, v138
	v_exp_f32_e32 v139, v139
	v_exp_f32_e32 v140, v140
	v_exp_f32_e32 v141, v141
	v_exp_f32_e32 v142, v142
	v_exp_f32_e32 v143, v143
	s_nop 0
	v_pk_add_f32 v[136:137], v[136:137], 1.0 op_sel_hi:[1,0]
	v_pk_add_f32 v[138:139], v[138:139], 1.0 op_sel_hi:[1,0]
	v_pk_add_f32 v[140:141], v[140:141], 1.0 op_sel_hi:[1,0]
	v_pk_add_f32 v[142:143], v[142:143], 1.0 op_sel_hi:[1,0]
	v_rcp_f32_e32 v136, v136
	v_rcp_f32_e32 v137, v137
	v_rcp_f32_e32 v138, v138
	v_rcp_f32_e32 v139, v139
	v_rcp_f32_e32 v140, v140
	v_rcp_f32_e32 v141, v141
	v_rcp_f32_e32 v142, v142
	v_rcp_f32_e32 v143, v143
	s_nop 0
	v_pk_mul_f32 v[68:69], v[68:69], v[136:137]
	v_pk_mul_f32 v[70:71], v[70:71], v[138:139]
	v_pk_mul_f32 v[64:65], v[64:65], v[140:141]
	v_pk_mul_f32 v[66:67], v[66:67], v[142:143]
	v_cvt_pk_bf16_f32 v68, v68, v69
	v_cvt_pk_bf16_f32 v69, v70, v71
	v_cvt_pk_bf16_f32 v70, v64, v65
	v_cvt_pk_bf16_f32 v71, v66, v67
	global_store_dwordx4 v[148:149], v[68:71], off
	s_mov_b64 vcc, 0x280000
	s_nop 0
	v_lshl_add_u64 v[144:145], v[144:145], 0, vcc
	v_lshl_add_u64 v[148:149], v[148:149], 0, vcc
	v_pk_mul_f32 v[136:137], v[60:61], v[60:61]
	v_pk_mul_f32 v[138:139], v[62:63], v[62:63]
	v_pk_mul_f32 v[140:141], v[56:57], v[56:57]
	v_pk_mul_f32 v[142:143], v[58:59], v[58:59]
	v_pk_fma_f32 v[136:137], v[136:137], v[244:245], v[246:247] op_sel_hi:[1,0,0]
	v_pk_fma_f32 v[138:139], v[138:139], v[244:245], v[246:247] op_sel_hi:[1,0,0]
	v_pk_fma_f32 v[140:141], v[140:141], v[244:245], v[246:247] op_sel_hi:[1,0,0]
	v_pk_fma_f32 v[142:143], v[142:143], v[244:245], v[246:247] op_sel_hi:[1,0,0]
	v_pk_mul_f32 v[136:137], v[136:137], v[60:61]
	v_pk_mul_f32 v[138:139], v[138:139], v[62:63]
	v_pk_mul_f32 v[140:141], v[140:141], v[56:57]
	v_pk_mul_f32 v[142:143], v[142:143], v[58:59]
	v_exp_f32_e32 v136, v136
	v_exp_f32_e32 v137, v137
	v_exp_f32_e32 v138, v138
	v_exp_f32_e32 v139, v139
	v_exp_f32_e32 v140, v140
	v_exp_f32_e32 v141, v141
	v_exp_f32_e32 v142, v142
	v_exp_f32_e32 v143, v143
	s_nop 0
	v_pk_add_f32 v[136:137], v[136:137], 1.0 op_sel_hi:[1,0]
	v_pk_add_f32 v[138:139], v[138:139], 1.0 op_sel_hi:[1,0]
	v_pk_add_f32 v[140:141], v[140:141], 1.0 op_sel_hi:[1,0]
	v_pk_add_f32 v[142:143], v[142:143], 1.0 op_sel_hi:[1,0]
	v_rcp_f32_e32 v136, v136
	v_rcp_f32_e32 v137, v137
	v_rcp_f32_e32 v138, v138
	v_rcp_f32_e32 v139, v139
	v_rcp_f32_e32 v140, v140
	v_rcp_f32_e32 v141, v141
	v_rcp_f32_e32 v142, v142
	v_rcp_f32_e32 v143, v143
	s_nop 0
	v_pk_mul_f32 v[60:61], v[60:61], v[136:137]
	v_pk_mul_f32 v[62:63], v[62:63], v[138:139]
	v_pk_mul_f32 v[56:57], v[56:57], v[140:141]
	v_pk_mul_f32 v[58:59], v[58:59], v[142:143]
	v_cvt_pk_bf16_f32 v60, v60, v61
	v_cvt_pk_bf16_f32 v61, v62, v63
	v_cvt_pk_bf16_f32 v62, v56, v57
	v_cvt_pk_bf16_f32 v63, v58, v59
	global_store_dwordx4 v[144:145], v[60:63], off
	v_pk_mul_f32 v[136:137], v[52:53], v[52:53]
	v_pk_mul_f32 v[138:139], v[54:55], v[54:55]
	v_pk_mul_f32 v[140:141], v[48:49], v[48:49]
	v_pk_mul_f32 v[142:143], v[50:51], v[50:51]
	v_pk_fma_f32 v[136:137], v[136:137], v[244:245], v[246:247] op_sel_hi:[1,0,0]
	v_pk_fma_f32 v[138:139], v[138:139], v[244:245], v[246:247] op_sel_hi:[1,0,0]
	v_pk_fma_f32 v[140:141], v[140:141], v[244:245], v[246:247] op_sel_hi:[1,0,0]
	v_pk_fma_f32 v[142:143], v[142:143], v[244:245], v[246:247] op_sel_hi:[1,0,0]
	v_pk_mul_f32 v[136:137], v[136:137], v[52:53]
	v_pk_mul_f32 v[138:139], v[138:139], v[54:55]
	v_pk_mul_f32 v[140:141], v[140:141], v[48:49]
	v_pk_mul_f32 v[142:143], v[142:143], v[50:51]
	v_exp_f32_e32 v136, v136
	v_exp_f32_e32 v137, v137
	v_exp_f32_e32 v138, v138
	v_exp_f32_e32 v139, v139
	v_exp_f32_e32 v140, v140
	v_exp_f32_e32 v141, v141
	v_exp_f32_e32 v142, v142
	v_exp_f32_e32 v143, v143
	s_nop 0
	v_pk_add_f32 v[136:137], v[136:137], 1.0 op_sel_hi:[1,0]
	v_pk_add_f32 v[138:139], v[138:139], 1.0 op_sel_hi:[1,0]
	v_pk_add_f32 v[140:141], v[140:141], 1.0 op_sel_hi:[1,0]
	v_pk_add_f32 v[142:143], v[142:143], 1.0 op_sel_hi:[1,0]
	v_rcp_f32_e32 v136, v136
	v_rcp_f32_e32 v137, v137
	v_rcp_f32_e32 v138, v138
	v_rcp_f32_e32 v139, v139
	v_rcp_f32_e32 v140, v140
	v_rcp_f32_e32 v141, v141
	v_rcp_f32_e32 v142, v142
	v_rcp_f32_e32 v143, v143
	s_nop 0
	v_pk_mul_f32 v[52:53], v[52:53], v[136:137]
	v_pk_mul_f32 v[54:55], v[54:55], v[138:139]
	v_pk_mul_f32 v[48:49], v[48:49], v[140:141]
	v_pk_mul_f32 v[50:51], v[50:51], v[142:143]
	v_cvt_pk_bf16_f32 v52, v52, v53
	v_cvt_pk_bf16_f32 v53, v54, v55
	v_cvt_pk_bf16_f32 v54, v48, v49
	v_cvt_pk_bf16_f32 v55, v50, v51
	global_store_dwordx4 v[148:149], v[52:55], off
	s_mov_b64 vcc, 0x80000
	s_nop 0
	v_lshl_add_u64 v[144:145], v[144:145], 0, vcc
	v_lshl_add_u64 v[148:149], v[148:149], 0, vcc
	v_pk_mul_f32 v[136:137], v[44:45], v[44:45]
	v_pk_mul_f32 v[138:139], v[46:47], v[46:47]
	v_pk_mul_f32 v[140:141], v[40:41], v[40:41]
	v_pk_mul_f32 v[142:143], v[42:43], v[42:43]
	v_pk_fma_f32 v[136:137], v[136:137], v[244:245], v[246:247] op_sel_hi:[1,0,0]
	v_pk_fma_f32 v[138:139], v[138:139], v[244:245], v[246:247] op_sel_hi:[1,0,0]
	v_pk_fma_f32 v[140:141], v[140:141], v[244:245], v[246:247] op_sel_hi:[1,0,0]
	v_pk_fma_f32 v[142:143], v[142:143], v[244:245], v[246:247] op_sel_hi:[1,0,0]
	v_pk_mul_f32 v[136:137], v[136:137], v[44:45]
	v_pk_mul_f32 v[138:139], v[138:139], v[46:47]
	v_pk_mul_f32 v[140:141], v[140:141], v[40:41]
	v_pk_mul_f32 v[142:143], v[142:143], v[42:43]
	v_exp_f32_e32 v136, v136
	v_exp_f32_e32 v137, v137
	v_exp_f32_e32 v138, v138
	v_exp_f32_e32 v139, v139
	v_exp_f32_e32 v140, v140
	v_exp_f32_e32 v141, v141
	v_exp_f32_e32 v142, v142
	v_exp_f32_e32 v143, v143
	s_nop 0
	v_pk_add_f32 v[136:137], v[136:137], 1.0 op_sel_hi:[1,0]
	v_pk_add_f32 v[138:139], v[138:139], 1.0 op_sel_hi:[1,0]
	v_pk_add_f32 v[140:141], v[140:141], 1.0 op_sel_hi:[1,0]
	v_pk_add_f32 v[142:143], v[142:143], 1.0 op_sel_hi:[1,0]
	v_rcp_f32_e32 v136, v136
	v_rcp_f32_e32 v137, v137
	v_rcp_f32_e32 v138, v138
	v_rcp_f32_e32 v139, v139
	v_rcp_f32_e32 v140, v140
	v_rcp_f32_e32 v141, v141
	v_rcp_f32_e32 v142, v142
	v_rcp_f32_e32 v143, v143
	s_nop 0
	v_pk_mul_f32 v[44:45], v[44:45], v[136:137]
	v_pk_mul_f32 v[46:47], v[46:47], v[138:139]
	v_pk_mul_f32 v[40:41], v[40:41], v[140:141]
	v_pk_mul_f32 v[42:43], v[42:43], v[142:143]
	v_cvt_pk_bf16_f32 v44, v44, v45
	v_cvt_pk_bf16_f32 v45, v46, v47
	v_cvt_pk_bf16_f32 v46, v40, v41
	v_cvt_pk_bf16_f32 v47, v42, v43
	global_store_dwordx4 v[144:145], v[44:47], off
	v_pk_mul_f32 v[136:137], v[36:37], v[36:37]
	v_pk_mul_f32 v[138:139], v[38:39], v[38:39]
	v_pk_mul_f32 v[140:141], v[32:33], v[32:33]
	v_pk_mul_f32 v[142:143], v[34:35], v[34:35]
	v_pk_fma_f32 v[136:137], v[136:137], v[244:245], v[246:247] op_sel_hi:[1,0,0]
	v_pk_fma_f32 v[138:139], v[138:139], v[244:245], v[246:247] op_sel_hi:[1,0,0]
	v_pk_fma_f32 v[140:141], v[140:141], v[244:245], v[246:247] op_sel_hi:[1,0,0]
	v_pk_fma_f32 v[142:143], v[142:143], v[244:245], v[246:247] op_sel_hi:[1,0,0]
	v_pk_mul_f32 v[136:137], v[136:137], v[36:37]
	v_pk_mul_f32 v[138:139], v[138:139], v[38:39]
	v_pk_mul_f32 v[140:141], v[140:141], v[32:33]
	v_pk_mul_f32 v[142:143], v[142:143], v[34:35]
	v_exp_f32_e32 v136, v136
	v_exp_f32_e32 v137, v137
	v_exp_f32_e32 v138, v138
	v_exp_f32_e32 v139, v139
	v_exp_f32_e32 v140, v140
	v_exp_f32_e32 v141, v141
	v_exp_f32_e32 v142, v142
	v_exp_f32_e32 v143, v143
	s_nop 0
	v_pk_add_f32 v[136:137], v[136:137], 1.0 op_sel_hi:[1,0]
	v_pk_add_f32 v[138:139], v[138:139], 1.0 op_sel_hi:[1,0]
	v_pk_add_f32 v[140:141], v[140:141], 1.0 op_sel_hi:[1,0]
	v_pk_add_f32 v[142:143], v[142:143], 1.0 op_sel_hi:[1,0]
	v_rcp_f32_e32 v136, v136
	v_rcp_f32_e32 v137, v137
	v_rcp_f32_e32 v138, v138
	v_rcp_f32_e32 v139, v139
	v_rcp_f32_e32 v140, v140
	v_rcp_f32_e32 v141, v141
	v_rcp_f32_e32 v142, v142
	v_rcp_f32_e32 v143, v143
	s_nop 0
	v_pk_mul_f32 v[36:37], v[36:37], v[136:137]
	v_pk_mul_f32 v[38:39], v[38:39], v[138:139]
	v_pk_mul_f32 v[32:33], v[32:33], v[140:141]
	v_pk_mul_f32 v[34:35], v[34:35], v[142:143]
	v_cvt_pk_bf16_f32 v36, v36, v37
	v_cvt_pk_bf16_f32 v37, v38, v39
	v_cvt_pk_bf16_f32 v38, v32, v33
	v_cvt_pk_bf16_f32 v39, v34, v35
	global_store_dwordx4 v[148:149], v[36:39], off
	s_mov_b64 vcc, 0x80000
	s_nop 0
	v_lshl_add_u64 v[144:145], v[144:145], 0, vcc
	v_lshl_add_u64 v[148:149], v[148:149], 0, vcc
	v_pk_mul_f32 v[136:137], v[28:29], v[28:29]
	v_pk_mul_f32 v[138:139], v[30:31], v[30:31]
	v_pk_mul_f32 v[140:141], v[24:25], v[24:25]
	v_pk_mul_f32 v[142:143], v[26:27], v[26:27]
	v_pk_fma_f32 v[136:137], v[136:137], v[244:245], v[246:247] op_sel_hi:[1,0,0]
	v_pk_fma_f32 v[138:139], v[138:139], v[244:245], v[246:247] op_sel_hi:[1,0,0]
	v_pk_fma_f32 v[140:141], v[140:141], v[244:245], v[246:247] op_sel_hi:[1,0,0]
	v_pk_fma_f32 v[142:143], v[142:143], v[244:245], v[246:247] op_sel_hi:[1,0,0]
	v_pk_mul_f32 v[136:137], v[136:137], v[28:29]
	v_pk_mul_f32 v[138:139], v[138:139], v[30:31]
	v_pk_mul_f32 v[140:141], v[140:141], v[24:25]
	v_pk_mul_f32 v[142:143], v[142:143], v[26:27]
	v_exp_f32_e32 v136, v136
	v_exp_f32_e32 v137, v137
	v_exp_f32_e32 v138, v138
	v_exp_f32_e32 v139, v139
	v_exp_f32_e32 v140, v140
	v_exp_f32_e32 v141, v141
	v_exp_f32_e32 v142, v142
	v_exp_f32_e32 v143, v143
	s_nop 0
	v_pk_add_f32 v[136:137], v[136:137], 1.0 op_sel_hi:[1,0]
	v_pk_add_f32 v[138:139], v[138:139], 1.0 op_sel_hi:[1,0]
	v_pk_add_f32 v[140:141], v[140:141], 1.0 op_sel_hi:[1,0]
	v_pk_add_f32 v[142:143], v[142:143], 1.0 op_sel_hi:[1,0]
	v_rcp_f32_e32 v136, v136
	v_rcp_f32_e32 v137, v137
	v_rcp_f32_e32 v138, v138
	v_rcp_f32_e32 v139, v139
	v_rcp_f32_e32 v140, v140
	v_rcp_f32_e32 v141, v141
	v_rcp_f32_e32 v142, v142
	v_rcp_f32_e32 v143, v143
	s_nop 0
	v_pk_mul_f32 v[28:29], v[28:29], v[136:137]
	v_pk_mul_f32 v[30:31], v[30:31], v[138:139]
	v_pk_mul_f32 v[24:25], v[24:25], v[140:141]
	v_pk_mul_f32 v[26:27], v[26:27], v[142:143]
	v_cvt_pk_bf16_f32 v28, v28, v29
	v_cvt_pk_bf16_f32 v29, v30, v31
	v_cvt_pk_bf16_f32 v30, v24, v25
	v_cvt_pk_bf16_f32 v31, v26, v27
	global_store_dwordx4 v[144:145], v[28:31], off
	v_pk_mul_f32 v[136:137], v[20:21], v[20:21]
	v_pk_mul_f32 v[138:139], v[22:23], v[22:23]
	v_pk_mul_f32 v[140:141], v[16:17], v[16:17]
	v_pk_mul_f32 v[142:143], v[18:19], v[18:19]
	v_pk_fma_f32 v[136:137], v[136:137], v[244:245], v[246:247] op_sel_hi:[1,0,0]
	v_pk_fma_f32 v[138:139], v[138:139], v[244:245], v[246:247] op_sel_hi:[1,0,0]
	v_pk_fma_f32 v[140:141], v[140:141], v[244:245], v[246:247] op_sel_hi:[1,0,0]
	v_pk_fma_f32 v[142:143], v[142:143], v[244:245], v[246:247] op_sel_hi:[1,0,0]
	v_pk_mul_f32 v[136:137], v[136:137], v[20:21]
	v_pk_mul_f32 v[138:139], v[138:139], v[22:23]
	v_pk_mul_f32 v[140:141], v[140:141], v[16:17]
	v_pk_mul_f32 v[142:143], v[142:143], v[18:19]
	v_exp_f32_e32 v136, v136
	v_exp_f32_e32 v137, v137
	v_exp_f32_e32 v138, v138
	v_exp_f32_e32 v139, v139
	v_exp_f32_e32 v140, v140
	v_exp_f32_e32 v141, v141
	v_exp_f32_e32 v142, v142
	v_exp_f32_e32 v143, v143
	s_nop 0
	v_pk_add_f32 v[136:137], v[136:137], 1.0 op_sel_hi:[1,0]
	v_pk_add_f32 v[138:139], v[138:139], 1.0 op_sel_hi:[1,0]
	v_pk_add_f32 v[140:141], v[140:141], 1.0 op_sel_hi:[1,0]
	v_pk_add_f32 v[142:143], v[142:143], 1.0 op_sel_hi:[1,0]
	v_rcp_f32_e32 v136, v136
	v_rcp_f32_e32 v137, v137
	v_rcp_f32_e32 v138, v138
	v_rcp_f32_e32 v139, v139
	v_rcp_f32_e32 v140, v140
	v_rcp_f32_e32 v141, v141
	v_rcp_f32_e32 v142, v142
	v_rcp_f32_e32 v143, v143
	s_nop 0
	v_pk_mul_f32 v[20:21], v[20:21], v[136:137]
	v_pk_mul_f32 v[22:23], v[22:23], v[138:139]
	v_pk_mul_f32 v[16:17], v[16:17], v[140:141]
	v_pk_mul_f32 v[18:19], v[18:19], v[142:143]
	v_cvt_pk_bf16_f32 v20, v20, v21
	v_cvt_pk_bf16_f32 v21, v22, v23
	v_cvt_pk_bf16_f32 v22, v16, v17
	v_cvt_pk_bf16_f32 v23, v18, v19
	global_store_dwordx4 v[148:149], v[20:23], off
	s_mov_b64 vcc, 0x80000
	s_nop 0
	v_lshl_add_u64 v[144:145], v[144:145], 0, vcc
	v_lshl_add_u64 v[148:149], v[148:149], 0, vcc
	v_pk_mul_f32 v[136:137], v[12:13], v[12:13]
	v_pk_mul_f32 v[138:139], v[14:15], v[14:15]
	v_pk_mul_f32 v[140:141], v[8:9], v[8:9]
	v_pk_mul_f32 v[142:143], v[10:11], v[10:11]
	v_pk_fma_f32 v[136:137], v[136:137], v[244:245], v[246:247] op_sel_hi:[1,0,0]
	v_pk_fma_f32 v[138:139], v[138:139], v[244:245], v[246:247] op_sel_hi:[1,0,0]
	v_pk_fma_f32 v[140:141], v[140:141], v[244:245], v[246:247] op_sel_hi:[1,0,0]
	v_pk_fma_f32 v[142:143], v[142:143], v[244:245], v[246:247] op_sel_hi:[1,0,0]
	v_pk_mul_f32 v[136:137], v[136:137], v[12:13]
	v_pk_mul_f32 v[138:139], v[138:139], v[14:15]
	v_pk_mul_f32 v[140:141], v[140:141], v[8:9]
	v_pk_mul_f32 v[142:143], v[142:143], v[10:11]
	v_exp_f32_e32 v136, v136
	v_exp_f32_e32 v137, v137
	v_exp_f32_e32 v138, v138
	v_exp_f32_e32 v139, v139
	v_exp_f32_e32 v140, v140
	v_exp_f32_e32 v141, v141
	v_exp_f32_e32 v142, v142
	v_exp_f32_e32 v143, v143
	s_nop 0
	v_pk_add_f32 v[136:137], v[136:137], 1.0 op_sel_hi:[1,0]
	v_pk_add_f32 v[138:139], v[138:139], 1.0 op_sel_hi:[1,0]
	v_pk_add_f32 v[140:141], v[140:141], 1.0 op_sel_hi:[1,0]
	v_pk_add_f32 v[142:143], v[142:143], 1.0 op_sel_hi:[1,0]
	v_rcp_f32_e32 v136, v136
	v_rcp_f32_e32 v137, v137
	v_rcp_f32_e32 v138, v138
	v_rcp_f32_e32 v139, v139
	v_rcp_f32_e32 v140, v140
	v_rcp_f32_e32 v141, v141
	v_rcp_f32_e32 v142, v142
	v_rcp_f32_e32 v143, v143
	s_nop 0
	v_pk_mul_f32 v[12:13], v[12:13], v[136:137]
	v_pk_mul_f32 v[14:15], v[14:15], v[138:139]
	v_pk_mul_f32 v[8:9], v[8:9], v[140:141]
	v_pk_mul_f32 v[10:11], v[10:11], v[142:143]
	v_cvt_pk_bf16_f32 v12, v12, v13
	v_cvt_pk_bf16_f32 v13, v14, v15
	v_cvt_pk_bf16_f32 v14, v8, v9
	v_cvt_pk_bf16_f32 v15, v10, v11
	global_store_dwordx4 v[144:145], v[12:15], off
	v_pk_mul_f32 v[136:137], v[4:5], v[4:5]
	v_pk_mul_f32 v[138:139], v[6:7], v[6:7]
	v_pk_mul_f32 v[140:141], v[0:1], v[0:1]
	v_pk_mul_f32 v[142:143], v[2:3], v[2:3]
	v_pk_fma_f32 v[136:137], v[136:137], v[244:245], v[246:247] op_sel_hi:[1,0,0]
	v_pk_fma_f32 v[138:139], v[138:139], v[244:245], v[246:247] op_sel_hi:[1,0,0]
	v_pk_fma_f32 v[140:141], v[140:141], v[244:245], v[246:247] op_sel_hi:[1,0,0]
	v_pk_fma_f32 v[142:143], v[142:143], v[244:245], v[246:247] op_sel_hi:[1,0,0]
	v_pk_mul_f32 v[136:137], v[136:137], v[4:5]
	v_pk_mul_f32 v[138:139], v[138:139], v[6:7]
	v_pk_mul_f32 v[140:141], v[140:141], v[0:1]
	v_pk_mul_f32 v[142:143], v[142:143], v[2:3]
	v_exp_f32_e32 v136, v136
	v_exp_f32_e32 v137, v137
	v_exp_f32_e32 v138, v138
	v_exp_f32_e32 v139, v139
	v_exp_f32_e32 v140, v140
	v_exp_f32_e32 v141, v141
	v_exp_f32_e32 v142, v142
	v_exp_f32_e32 v143, v143
	s_nop 0
	v_pk_add_f32 v[136:137], v[136:137], 1.0 op_sel_hi:[1,0]
	v_pk_add_f32 v[138:139], v[138:139], 1.0 op_sel_hi:[1,0]
	v_pk_add_f32 v[140:141], v[140:141], 1.0 op_sel_hi:[1,0]
	v_pk_add_f32 v[142:143], v[142:143], 1.0 op_sel_hi:[1,0]
	v_rcp_f32_e32 v136, v136
	v_rcp_f32_e32 v137, v137
	v_rcp_f32_e32 v138, v138
	v_rcp_f32_e32 v139, v139
	v_rcp_f32_e32 v140, v140
	v_rcp_f32_e32 v141, v141
	v_rcp_f32_e32 v142, v142
	v_rcp_f32_e32 v143, v143
	s_nop 0
	v_pk_mul_f32 v[4:5], v[4:5], v[136:137]
	v_pk_mul_f32 v[6:7], v[6:7], v[138:139]
	v_pk_mul_f32 v[0:1], v[0:1], v[140:141]
	v_pk_mul_f32 v[2:3], v[2:3], v[142:143]
	v_cvt_pk_bf16_f32 v4, v4, v5
	v_cvt_pk_bf16_f32 v5, v6, v7
	v_cvt_pk_bf16_f32 v6, v0, v1
	v_cvt_pk_bf16_f32 v7, v2, v3
	global_store_dwordx4 v[148:149], v[4:7], off
	s_mov_b64 s[0:1], 0
